# v31 + branch-free W_mla conversion (one load round trip) + scan U/glast fetched two steps ahead
# speedup vs baseline: 1.0132x; 1.0041x over previous
; #define LAS __attribute__((address_space(3)))
; __device__ __forceinline__ void gdn_scan_item(const Ctx& a, int l, int b, int h, int half, LAS unsigned char* lds, int variant) {
;     ...
;     f32x16 S[4];
; #pragma unroll
;     for (int kb = 0; kb < 4; ++kb)
; #pragma unroll
;         for (int r = 0; r < 16; ++r) S[kb][r] = 0.f;
;     const int dv0 = half * 32;
;     u32x4 U[2][2]; float gl_next = 0.f;
;     ...
;     if (loader) { GS_LOAD(0, pfA); GS_STORE(0, pfA); GS_LOAD(1, pfB); } else if (wv < 1) { GS_LOADU(0); }
;     ...
;         for (int n = 0; n < 128; ++n) {
;             const int bufi = n & 1;
;             if (variant == 2) { GS_BAR(); continue; }
;             LAS unsigned char* Bf = lds + bufi * GS_BUF;
;             const LAS bf16_t* Wb = (const LAS bf16_t*)(Bf + GS_W); const LAS bf16_t* Qb = (const LAS bf16_t*)(Bf + GS_Q);
;             const LAS bf16_t* Kt = (const LAS bf16_t*)(Bf + GS_K); const LAS bf16_t* QKb = (const LAS bf16_t*)(Bf + GS_QK);
;             f32x16 vn[2], o[2];
;             const float gl = gl_next;
; #pragma unroll
;             for (int tb = 0; tb < 2; ++tb)
; #pragma unroll
;                 for (int r = 0; r < 16; ++r) { vn[tb][r] = 0.f; o[tb][r] = 0.f; }
;             bf16x8 aop[16];
; #pragma unroll
;             for (int kb = 0; kb < 4; ++kb) {
; #pragma unroll
;                 for (int c = 0; c < 2; ++c)
; #pragma unroll
;                     for (int tb = 0; tb < 2; ++tb) {
;                         aop[c * 2 + tb] = lds_a2(Wb + (tb * 32 + l32) * 132 + kb * 32 + c * 16 + hb * 4);
;                         aop[4 + c * 2 + tb] = lds_a2(Qb + (tb * 32 + l32) * 132 + kb * 32 + c * 16 + hb * 4);
;                     }
;                 __builtin_amdgcn_sched_barrier(0);
; #pragma unroll
;                 for (int c = 0; c < 2; ++c) {
;                     bf16x8 sb = pack8(S[kb], c);
; #pragma unroll
;                     for (int tb = 0; tb < 2; ++tb) {
;                         vn[tb] = __builtin_amdgcn_mfma_f32_32x32x16_bf16(aop[c * 2 + tb], sb, vn[tb], 0, 0, 0);
;                         o[tb] = __builtin_amdgcn_mfma_f32_32x32x16_bf16(aop[4 + c * 2 + tb], sb, o[tb], 0, 0, 0);
;                     }
;                 }
;                 __builtin_amdgcn_sched_barrier(0);
;             }
;             bf16x8 vb[2][2];
; #pragma unroll
;             for (int tb = 0; tb < 2; ++tb) {
; #pragma unroll
.Lsc0_entry:
	s_lshr_b32 s42, s2, 2
	s_and_b32 s43, s2, 3
	s_lshl_b32 s8, s42, 9
	s_add_u32 s8, s8, s43
	s_lshl_b32 s8, s8, 12
	s_add_u32 s36, s16, 0xe8f4200
	s_addc_u32 s37, s17, 0
	s_add_u32 s36, s36, s8
	s_addc_u32 s37, s37, 0
	s_lshl_b32 s8, s42, 9
	s_add_u32 s38, s16, 0x58f0000
	s_addc_u32 s39, s17, 0
	s_add_u32 s38, s38, s8
	s_addc_u32 s39, s39, 0
	v_and_b32 v1, 31, v195
	v_lshrrev_b32 v2, 5, v195
	v_lshlrev_b32 v186, 5, v195
	v_mul_u32_u24 v184, 264, v1
	v_lshl_add_u32 v184, v2, 3, v184
	v_mul_u32_u24 v185, 136, v1
	v_lshl_add_u32 v185, v2, 3, v185
	v_lshlrev_b32 v188, 4, v195
	v_add_u32 v189, 136192, v188
	v_add_u32 v188, 128000, v188
	v_mov_b32 v3, 0
	global_load_dwordx4 v[162:165], v186, s[36:37] offset:0
	global_load_dwordx4 v[166:169], v186, s[36:37] offset:16
	global_load_dwordx4 v[170:173], v186, s[36:37] offset:2048
	global_load_dwordx4 v[174:177], v186, s[36:37] offset:2064
	global_load_dword v181, v3, s[38:39]
	s_add_u32 s36, s36, 0x4000
	s_addc_u32 s37, s37, 0
	s_add_u32 s38, s38, 4
	s_addc_u32 s39, s39, 0
	global_load_dwordx4 v[4:7], v186, s[36:37] offset:0
	global_load_dwordx4 v[8:11], v186, s[36:37] offset:16
	global_load_dwordx4 v[12:15], v186, s[36:37] offset:2048
	global_load_dwordx4 v[190:193], v186, s[36:37] offset:2064
	global_load_dword v2, v3, s[38:39]
	s_add_u32 s36, s36, 0x4000
	s_addc_u32 s37, s37, 0
	s_add_u32 s38, s38, 4
	s_addc_u32 s39, s39, 0
	v_mov_b32 v16, 0
	v_mov_b32 v17, 0
	v_mov_b32 v18, 0
	v_mov_b32 v19, 0
	v_mov_b32 v20, 0
	v_mov_b32 v21, 0
	v_mov_b32 v22, 0
	v_mov_b32 v23, 0
	v_mov_b32 v24, 0
	v_mov_b32 v25, 0
	v_mov_b32 v26, 0
	v_mov_b32 v27, 0
	v_mov_b32 v28, 0
	v_mov_b32 v29, 0
	v_mov_b32 v30, 0
	v_mov_b32 v31, 0
	v_mov_b32 v32, 0
	v_mov_b32 v33, 0
	v_mov_b32 v34, 0
	v_mov_b32 v35, 0
	v_mov_b32 v36, 0
	v_mov_b32 v37, 0
	v_mov_b32 v38, 0
	v_mov_b32 v39, 0
	v_mov_b32 v40, 0
	v_mov_b32 v41, 0
	v_mov_b32 v42, 0
	v_mov_b32 v43, 0
	v_mov_b32 v44, 0
	v_mov_b32 v45, 0
	v_mov_b32 v46, 0
	v_mov_b32 v47, 0
	v_mov_b32 v48, 0
	v_mov_b32 v49, 0
	v_mov_b32 v50, 0
	v_mov_b32 v51, 0
	v_mov_b32 v52, 0
	v_mov_b32 v53, 0
	v_mov_b32 v54, 0
	v_mov_b32 v55, 0
	v_mov_b32 v56, 0
	v_mov_b32 v57, 0
	v_mov_b32 v58, 0
	v_mov_b32 v59, 0
	v_mov_b32 v60, 0
	v_mov_b32 v61, 0
	v_mov_b32 v62, 0
	v_mov_b32 v63, 0
	v_mov_b32 v64, 0
	v_mov_b32 v65, 0
	v_mov_b32 v66, 0
	v_mov_b32 v67, 0
	v_mov_b32 v68, 0
	v_mov_b32 v69, 0
	v_mov_b32 v70, 0
	v_mov_b32 v71, 0
	v_mov_b32 v72, 0
	v_mov_b32 v73, 0
	v_mov_b32 v74, 0
	v_mov_b32 v75, 0
	v_mov_b32 v76, 0
	v_mov_b32 v77, 0
	v_mov_b32 v78, 0
	v_mov_b32 v79, 0
	v_mov_b32 v112, 0
	v_mov_b32 v113, 0
	v_mov_b32 v114, 0
	v_mov_b32 v115, 0
	v_mov_b32 v116, 0
	v_mov_b32 v117, 0
	v_mov_b32 v118, 0
	v_mov_b32 v119, 0
	v_mov_b32 v120, 0
	v_mov_b32 v121, 0
	v_mov_b32 v122, 0
	v_mov_b32 v123, 0
	v_mov_b32 v124, 0
	v_mov_b32 v125, 0
	v_mov_b32 v126, 0
	v_mov_b32 v127, 0
	v_mov_b32 v128, 0
	v_mov_b32 v129, 0
	v_mov_b32 v130, 0
	v_mov_b32 v131, 0
	v_mov_b32 v132, 0
	v_mov_b32 v133, 0
	v_mov_b32 v134, 0
	v_mov_b32 v135, 0
	v_mov_b32 v136, 0
	v_mov_b32 v137, 0
	v_mov_b32 v138, 0
	v_mov_b32 v139, 0
	v_mov_b32 v140, 0
	v_mov_b32 v141, 0
	v_mov_b32 v142, 0
	v_mov_b32 v143, 0
	s_mov_b32 s26, 0
	s_mov_b32 s30, 0xea00
	s_movk_i32 s12, 0x2000
	s_movk_i32 s13, 0x1000
.Lsc0_loop:
	s_waitcnt vmcnt(5)
	v_mul_f32 v187, 0x3fb8aa3b, v181
	v_exp_f32 v187, v187
	s_nop 7
	s_nop 0
	v_lshlrev_b32 v80, 16, v162
	v_and_b32 v81, 0xffff0000, v162
	v_lshlrev_b32 v82, 16, v163
	v_and_b32 v83, 0xffff0000, v163
	v_lshlrev_b32 v84, 16, v164
	v_and_b32 v85, 0xffff0000, v164
	v_lshlrev_b32 v86, 16, v165
	v_and_b32 v87, 0xffff0000, v165
	v_lshlrev_b32 v88, 16, v166
	v_and_b32 v89, 0xffff0000, v166
	v_lshlrev_b32 v90, 16, v167
	v_and_b32 v91, 0xffff0000, v167
	v_lshlrev_b32 v92, 16, v168
	v_and_b32 v93, 0xffff0000, v168
	v_lshlrev_b32 v94, 16, v169
	v_and_b32 v95, 0xffff0000, v169
	v_lshlrev_b32 v96, 16, v170
	v_and_b32 v97, 0xffff0000, v170
	v_lshlrev_b32 v98, 16, v171
	v_and_b32 v99, 0xffff0000, v171
	v_lshlrev_b32 v100, 16, v172
	v_and_b32 v101, 0xffff0000, v172
	v_lshlrev_b32 v102, 16, v173
	v_and_b32 v103, 0xffff0000, v173
	v_lshlrev_b32 v104, 16, v174
	v_and_b32 v105, 0xffff0000, v174
	v_lshlrev_b32 v106, 16, v175
	v_and_b32 v107, 0xffff0000, v175
	v_lshlrev_b32 v108, 16, v176
	v_and_b32 v109, 0xffff0000, v176
	v_lshlrev_b32 v110, 16, v177
	v_and_b32 v111, 0xffff0000, v177
	global_load_dwordx4 v[162:165], v186, s[36:37] offset:0
	global_load_dwordx4 v[166:169], v186, s[36:37] offset:16
	global_load_dwordx4 v[170:173], v186, s[36:37] offset:2048
	global_load_dwordx4 v[174:177], v186, s[36:37] offset:2064
	global_load_dword v181, v3, s[38:39]
	s_add_u32 s36, s36, 0x4000
	s_addc_u32 s37, s37, 0
	s_add_u32 s38, s38, 4
	s_addc_u32 s39, s39, 0
	ds_read_b64 v[200:201], v184 offset:0
	ds_read_b64 v[202:203], v184 offset:16
	ds_read_b64 v[204:205], v184 offset:8448
	ds_read_b64 v[206:207], v184 offset:8464
	ds_read_b64 v[208:209], v184 offset:32
	ds_read_b64 v[210:211], v184 offset:48
	ds_read_b64 v[212:213], v184 offset:8480
	ds_read_b64 v[214:215], v184 offset:8496
	ds_read_b64 v[216:217], v184 offset:64
	ds_read_b64 v[218:219], v184 offset:80
	s_waitcnt lgkmcnt(8)
	v_mfma_f32_32x32x16_bf16 v[80:95], v[200:203], v[112:115], v[80:95]
	ds_read_b64 v[220:221], v184 offset:8512
	ds_read_b64 v[222:223], v184 offset:8528
	v_mul_f32 v16, v16, v187
	v_mul_f32 v17, v17, v187
	v_mul_f32 v18, v18, v187
	v_mul_f32 v19, v19, v187
	s_waitcnt lgkmcnt(8)
	v_mfma_f32_32x32x16_bf16 v[96:111], v[204:207], v[112:115], v[96:111]
	ds_read_b64 v[200:201], v184 offset:96
	ds_read_b64 v[202:203], v184 offset:112
	v_mul_f32 v20, v20, v187
	v_mul_f32 v21, v21, v187
	v_mul_f32 v22, v22, v187
	v_mul_f32 v23, v23, v187
	s_waitcnt lgkmcnt(8)
; __device__ __forceinline__ void gdn_scan_item(const Ctx& a, int l, int b, int h, int half, LAS unsigned char* lds, int variant) {
;     ...
;             for (int kb = 0; kb < 4; ++kb) {
; #pragma unroll
;                 for (int c = 0; c < 2; ++c)
; #pragma unroll
;                     for (int tb = 0; tb < 2; ++tb) {
;                         aop[c * 2 + tb] = lds_a2(Wb + (tb * 32 + l32) * 132 + kb * 32 + c * 16 + hb * 4);
;                         aop[4 + c * 2 + tb] = lds_a2(Qb + (tb * 32 + l32) * 132 + kb * 32 + c * 16 + hb * 4);
;                     }
;                 __builtin_amdgcn_sched_barrier(0);
; #pragma unroll
;                 for (int c = 0; c < 2; ++c) {
;                     bf16x8 sb = pack8(S[kb], c);
; #pragma unroll
;                     for (int tb = 0; tb < 2; ++tb) {
;                         vn[tb] = __builtin_amdgcn_mfma_f32_32x32x16_bf16(aop[c * 2 + tb], sb, vn[tb], 0, 0, 0);
;                         o[tb] = __builtin_amdgcn_mfma_f32_32x32x16_bf16(aop[4 + c * 2 + tb], sb, o[tb], 0, 0, 0);
;                     }
;                 }
;                 __builtin_amdgcn_sched_barrier(0);
;             }
;             bf16x8 vb[2][2];
; #pragma unroll
;             for (int tb = 0; tb < 2; ++tb) {
; #pragma unroll
;                 for (int r = 0; r < 16; ++r) { unsigned uw = U[tb][r >> 3][(r >> 1) & 3]; vn[tb][r] = ((r & 1) ? hi_bf(uw) : lo_bf(uw)) - vn[tb][r]; }
;                 vb[tb][0] = pack8(vn[tb], 0); vb[tb][1] = pack8(vn[tb], 1);
;             }
;             __builtin_amdgcn_sched_barrier(0);
;             { const int n1_ = (n + 1 < 128) ? n + 1 : 127; GS_LOADU(n1_); }
;             bf16x8 qop[8];
; #pragma unroll
;             for (int kb = 0; kb < 4; ++kb)
; #pragma unroll
;                 for (int tb2 = 0; tb2 < 2; ++tb2)
; #pragma unroll
;                     for (int c = 0; c < 2; ++c) aop[(kb * 2 + tb2) * 2 + c] = lds_a2(Kt + (kb * 32 + l32) * 68 + tb2 * 32 + c * 16 + hb * 4);
; #pragma unroll
;             for (int kb = 0; kb < 4; ++kb)
; #pragma unroll
;                 for (int r = 0; r < 16; ++r) S[kb][r] *= gl;
;             __builtin_amdgcn_sched_barrier(0);
; #pragma unroll
;             for (int tb2 = 0; tb2 < 2; ++tb2)
; #pragma unroll
;                 for (int c = 0; c < 2; ++c)
; #pragma unroll
;                     for (int kb = 0; kb < 4; ++kb)
	v_mfma_f32_32x32x16_bf16 v[80:95], v[208:211], v[116:119], v[80:95]
	ds_read_b64 v[204:205], v184 offset:8544
	ds_read_b64 v[206:207], v184 offset:8560
	v_mul_f32 v24, v24, v187
	v_mul_f32 v25, v25, v187
	v_mul_f32 v26, v26, v187
	v_mul_f32 v27, v27, v187
	s_waitcnt lgkmcnt(8)
	v_mfma_f32_32x32x16_bf16 v[96:111], v[212:215], v[116:119], v[96:111]
	ds_read_b64 v[208:209], v184 offset:128
	ds_read_b64 v[210:211], v184 offset:144
	v_mul_f32 v28, v28, v187
	v_mul_f32 v29, v29, v187
	v_mul_f32 v30, v30, v187
	v_mul_f32 v31, v31, v187
	s_waitcnt lgkmcnt(8)
	v_mfma_f32_32x32x16_bf16 v[80:95], v[216:219], v[120:123], v[80:95]
	ds_read_b64 v[212:213], v184 offset:8576
	ds_read_b64 v[214:215], v184 offset:8592
	v_mul_f32 v32, v32, v187
	v_mul_f32 v33, v33, v187
	v_mul_f32 v34, v34, v187
	v_mul_f32 v35, v35, v187
	s_waitcnt lgkmcnt(8)
	v_mfma_f32_32x32x16_bf16 v[96:111], v[220:223], v[120:123], v[96:111]
	ds_read_b64 v[216:217], v184 offset:160
	ds_read_b64 v[218:219], v184 offset:176
	v_mul_f32 v36, v36, v187
	v_mul_f32 v37, v37, v187
	v_mul_f32 v38, v38, v187
	v_mul_f32 v39, v39, v187
	s_waitcnt lgkmcnt(8)
	v_mfma_f32_32x32x16_bf16 v[80:95], v[200:203], v[124:127], v[80:95]
	ds_read_b64 v[220:221], v184 offset:8608
	ds_read_b64 v[222:223], v184 offset:8624
	v_mul_f32 v40, v40, v187
	v_mul_f32 v41, v41, v187
	v_mul_f32 v42, v42, v187
	v_mul_f32 v43, v43, v187
	s_waitcnt lgkmcnt(8)
	v_mfma_f32_32x32x16_bf16 v[96:111], v[204:207], v[124:127], v[96:111]
	ds_read_b64 v[200:201], v184 offset:192
	ds_read_b64 v[202:203], v184 offset:208
	v_mul_f32 v44, v44, v187
	v_mul_f32 v45, v45, v187
	v_mul_f32 v46, v46, v187
	v_mul_f32 v47, v47, v187
	s_waitcnt lgkmcnt(8)
	v_mfma_f32_32x32x16_bf16 v[80:95], v[208:211], v[128:131], v[80:95]
	ds_read_b64 v[204:205], v184 offset:8640
	ds_read_b64 v[206:207], v184 offset:8656
	v_mul_f32 v48, v48, v187
	v_mul_f32 v49, v49, v187
	v_mul_f32 v50, v50, v187
	v_mul_f32 v51, v51, v187
	s_waitcnt lgkmcnt(8)
	v_mfma_f32_32x32x16_bf16 v[96:111], v[212:215], v[128:131], v[96:111]
	ds_read_b64 v[208:209], v184 offset:224
	ds_read_b64 v[210:211], v184 offset:240
	v_mul_f32 v52, v52, v187
	v_mul_f32 v53, v53, v187
	v_mul_f32 v54, v54, v187
	v_mul_f32 v55, v55, v187
	s_waitcnt lgkmcnt(8)
	v_mfma_f32_32x32x16_bf16 v[80:95], v[216:219], v[132:135], v[80:95]
	ds_read_b64 v[212:213], v184 offset:8672
	ds_read_b64 v[214:215], v184 offset:8688
	v_mul_f32 v56, v56, v187
	v_mul_f32 v57, v57, v187
	v_mul_f32 v58, v58, v187
	v_mul_f32 v59, v59, v187
	s_waitcnt lgkmcnt(8)
	v_mfma_f32_32x32x16_bf16 v[96:111], v[220:223], v[132:135], v[96:111]
	v_mul_f32 v60, v60, v187
	v_mul_f32 v61, v61, v187
	v_mul_f32 v62, v62, v187
	v_mul_f32 v63, v63, v187
	s_waitcnt lgkmcnt(6)
	v_mfma_f32_32x32x16_bf16 v[80:95], v[200:203], v[136:139], v[80:95]
	v_mul_f32 v64, v64, v187
	v_mul_f32 v65, v65, v187
	v_mul_f32 v66, v66, v187
	v_mul_f32 v67, v67, v187
	s_waitcnt lgkmcnt(4)
	v_mfma_f32_32x32x16_bf16 v[96:111], v[204:207], v[136:139], v[96:111]
	v_mul_f32 v68, v68, v187
	v_mul_f32 v69, v69, v187
	v_mul_f32 v70, v70, v187
	v_mul_f32 v71, v71, v187
	s_waitcnt lgkmcnt(2)
	v_mfma_f32_32x32x16_bf16 v[80:95], v[208:211], v[140:143], v[80:95]
	v_mul_f32 v72, v72, v187
	v_mul_f32 v73, v73, v187
	v_mul_f32 v74, v74, v187
	v_mul_f32 v75, v75, v187
	s_waitcnt lgkmcnt(0)
	v_mfma_f32_32x32x16_bf16 v[96:111], v[212:215], v[140:143], v[96:111]
	v_mul_f32 v76, v76, v187
	v_mul_f32 v77, v77, v187
	v_mul_f32 v78, v78, v187
	v_mul_f32 v79, v79, v187
	ds_read_b64 v[224:225], v185 offset:33792
	ds_read_b64 v[226:227], v185 offset:33808
	ds_read_b64 v[228:229], v185 offset:38144
	ds_read_b64 v[230:231], v185 offset:38160
	ds_read_b64 v[232:233], v185 offset:42496
	ds_read_b64 v[234:235], v185 offset:42512
	ds_read_b64 v[236:237], v185 offset:46848
	ds_read_b64 v[238:239], v185 offset:46864
	ds_read_b64 v[240:241], v185 offset:33824
	ds_read_b64 v[242:243], v185 offset:33840
	v_cvt_pk_bf16_f32 v146, v80, v81
	v_cvt_pk_bf16_f32 v147, v82, v83
	v_cvt_pk_bf16_f32 v148, v84, v85
	v_cvt_pk_bf16_f32 v149, v86, v87
	v_cvt_pk_bf16_f32 v150, v88, v89
	v_cvt_pk_bf16_f32 v151, v90, v91
	v_cvt_pk_bf16_f32 v152, v92, v93
	v_cvt_pk_bf16_f32 v153, v94, v95
	v_cvt_pk_bf16_f32 v154, v96, v97
	v_cvt_pk_bf16_f32 v155, v98, v99
	v_cvt_pk_bf16_f32 v156, v100, v101
	v_cvt_pk_bf16_f32 v157, v102, v103
	v_cvt_pk_bf16_f32 v158, v104, v105
	v_cvt_pk_bf16_f32 v159, v106, v107
	v_cvt_pk_bf16_f32 v160, v108, v109
	v_cvt_pk_bf16_f32 v161, v110, v111
	ds_write_b128 v189, v[146:149] offset:0
	ds_write_b128 v189, v[150:153] offset:1024
	ds_write_b128 v189, v[154:157] offset:2048
	ds_write_b128 v189, v[158:161] offset:3072
	s_waitcnt lgkmcnt(12)
	v_mfma_f32_32x32x16_bf16 v[16:31], v[224:227], v[146:149], v[16:31]
	ds_read_b64 v[244:245], v185 offset:38176
	ds_read_b64 v[246:247], v185 offset:38192
	s_waitcnt lgkmcnt(12)
	v_mfma_f32_32x32x16_bf16 v[32:47], v[228:231], v[146:149], v[32:47]
	ds_read_b64 v[248:249], v185 offset:42528
	ds_read_b64 v[250:251], v185 offset:42544
	s_waitcnt lgkmcnt(12)
	v_mfma_f32_32x32x16_bf16 v[48:63], v[232:235], v[146:149], v[48:63]
	ds_read_b64 v[224:225], v185 offset:46880
	ds_read_b64 v[226:227], v185 offset:46896
	s_waitcnt lgkmcnt(12)
	v_mfma_f32_32x32x16_bf16 v[64:79], v[236:239], v[146:149], v[64:79]
	ds_read_b64 v[228:229], v185 offset:33856
	ds_read_b64 v[230:231], v185 offset:33872
	s_waitcnt lgkmcnt(12)
	v_mfma_f32_32x32x16_bf16 v[16:31], v[240:243], v[150:153], v[16:31]
	ds_read_b64 v[232:233], v185 offset:38208
	ds_read_b64 v[234:235], v185 offset:38224
	s_waitcnt lgkmcnt(8)
	v_mfma_f32_32x32x16_bf16 v[32:47], v[244:247], v[150:153], v[32:47]
	ds_read_b64 v[236:237], v185 offset:42560
	ds_read_b64 v[238:239], v185 offset:42576
	s_waitcnt lgkmcnt(8)
; __device__ __forceinline__ float lo_bf(unsigned u) { return __uint_as_float(u << 16); }
; __device__ __forceinline__ void gdn_scan_item(const Ctx& a, int l, int b, int h, int half, LAS unsigned char* lds, int variant) {
;     ...
;                 for (int r = 0; r < 16; ++r) { unsigned uw = U[tb][r >> 3][(r >> 1) & 3]; vn[tb][r] = ((r & 1) ? hi_bf(uw) : lo_bf(uw)) - vn[tb][r]; }
;                 vb[tb][0] = pack8(vn[tb], 0); vb[tb][1] = pack8(vn[tb], 1);
;             }
;             __builtin_amdgcn_sched_barrier(0);
;             { const int n1_ = (n + 1 < 128) ? n + 1 : 127; GS_LOADU(n1_); }
;             bf16x8 qop[8];
; #pragma unroll
;             for (int kb = 0; kb < 4; ++kb)
; #pragma unroll
;                 for (int tb2 = 0; tb2 < 2; ++tb2)
; #pragma unroll
;                     for (int c = 0; c < 2; ++c) aop[(kb * 2 + tb2) * 2 + c] = lds_a2(Kt + (kb * 32 + l32) * 68 + tb2 * 32 + c * 16 + hb * 4);
; #pragma unroll
;             for (int kb = 0; kb < 4; ++kb)
; #pragma unroll
;                 for (int r = 0; r < 16; ++r) S[kb][r] *= gl;
;             __builtin_amdgcn_sched_barrier(0);
; #pragma unroll
;             for (int tb2 = 0; tb2 < 2; ++tb2)
; #pragma unroll
;                 for (int c = 0; c < 2; ++c)
; #pragma unroll
;                     for (int kb = 0; kb < 4; ++kb)
;                         S[kb] = __builtin_amdgcn_mfma_f32_32x32x16_bf16(aop[(kb * 2 + tb2) * 2 + c], vb[tb2][c], S[kb], 0, 0, 0);
;             __builtin_amdgcn_sched_barrier(0);
; #pragma unroll
;             for (int tb2 = 0; tb2 < 2; ++tb2)
; #pragma unroll
;                 for (int c = 0; c < 2; ++c)
; #pragma unroll
;                     for (int tb = 0; tb < 2; ++tb) qop[(tb2 * 2 + c) * 2 + tb] = lds_a2(QKb + (tb * 32 + l32) * 68 + tb2 * 32 + c * 16 + hb * 4);
;             __builtin_amdgcn_sched_barrier(0);
; #pragma unroll
;             for (int tb2 = 0; tb2 < 2; ++tb2)
; #pragma unroll
;                 for (int c = 0; c < 2; ++c)
; #pragma unroll
;                     for (int tb = 0; tb < 2; ++tb) o[tb] = __builtin_amdgcn_mfma_f32_32x32x16_bf16(qop[(tb2 * 2 + c) * 2 + tb], vb[tb2][c], o[tb], 0, 0, 0);
;             __builtin_amdgcn_sched_barrier(0);
;             {
;                 bf16_t* op = br + ((size_t)b * SEQ + n * 64) * BR + 512 + h * 128 + dv0 + l32;
; #pragma unroll
;                 for (int tb = 0; tb < 2; ++tb)
; #pragma unroll
	v_mfma_f32_32x32x16_bf16 v[48:63], v[248:251], v[150:153], v[48:63]
	ds_read_b64 v[240:241], v185 offset:46912
	ds_read_b64 v[242:243], v185 offset:46928
	s_waitcnt lgkmcnt(8)
	v_mfma_f32_32x32x16_bf16 v[64:79], v[224:227], v[150:153], v[64:79]
	ds_read_b64 v[244:245], v185 offset:33888
	ds_read_b64 v[246:247], v185 offset:33904
	s_waitcnt lgkmcnt(8)
	v_mfma_f32_32x32x16_bf16 v[16:31], v[228:231], v[154:157], v[16:31]
	ds_read_b64 v[248:249], v185 offset:38240
	ds_read_b64 v[250:251], v185 offset:38256
	s_waitcnt lgkmcnt(8)
	v_mfma_f32_32x32x16_bf16 v[32:47], v[232:235], v[154:157], v[32:47]
	ds_read_b64 v[224:225], v185 offset:42592
	ds_read_b64 v[226:227], v185 offset:42608
	s_waitcnt lgkmcnt(8)
	v_mfma_f32_32x32x16_bf16 v[48:63], v[236:239], v[154:157], v[48:63]
	ds_read_b64 v[228:229], v185 offset:46944
	ds_read_b64 v[230:231], v185 offset:46960
	s_waitcnt lgkmcnt(8)
	v_mfma_f32_32x32x16_bf16 v[64:79], v[240:243], v[154:157], v[64:79]
	s_waitcnt lgkmcnt(6)
	v_mfma_f32_32x32x16_bf16 v[16:31], v[244:247], v[158:161], v[16:31]
	s_waitcnt lgkmcnt(4)
	v_mfma_f32_32x32x16_bf16 v[32:47], v[248:251], v[158:161], v[32:47]
	s_waitcnt lgkmcnt(2)
	v_mfma_f32_32x32x16_bf16 v[48:63], v[224:227], v[158:161], v[48:63]
	s_waitcnt lgkmcnt(0)
	v_mfma_f32_32x32x16_bf16 v[64:79], v[228:231], v[158:161], v[64:79]
	s_nop 5
	v_cvt_pk_bf16_f32 v112, -v16, -v17
	v_cvt_pk_bf16_f32 v113, -v18, -v19
	v_cvt_pk_bf16_f32 v114, -v20, -v21
	v_cvt_pk_bf16_f32 v115, -v22, -v23
	v_cvt_pk_bf16_f32 v116, -v24, -v25
	v_cvt_pk_bf16_f32 v117, -v26, -v27
	v_cvt_pk_bf16_f32 v118, -v28, -v29
	v_cvt_pk_bf16_f32 v119, -v30, -v31
	v_cvt_pk_bf16_f32 v120, -v32, -v33
	v_cvt_pk_bf16_f32 v121, -v34, -v35
	v_cvt_pk_bf16_f32 v122, -v36, -v37
	v_cvt_pk_bf16_f32 v123, -v38, -v39
	v_cvt_pk_bf16_f32 v124, -v40, -v41
	v_cvt_pk_bf16_f32 v125, -v42, -v43
	v_cvt_pk_bf16_f32 v126, -v44, -v45
	v_cvt_pk_bf16_f32 v127, -v46, -v47
	v_cvt_pk_bf16_f32 v128, -v48, -v49
	v_cvt_pk_bf16_f32 v129, -v50, -v51
	v_cvt_pk_bf16_f32 v130, -v52, -v53
	v_cvt_pk_bf16_f32 v131, -v54, -v55
	v_cvt_pk_bf16_f32 v132, -v56, -v57
	v_cvt_pk_bf16_f32 v133, -v58, -v59
	v_cvt_pk_bf16_f32 v134, -v60, -v61
	v_cvt_pk_bf16_f32 v135, -v62, -v63
	v_cvt_pk_bf16_f32 v136, -v64, -v65
	v_cvt_pk_bf16_f32 v137, -v66, -v67
	v_cvt_pk_bf16_f32 v138, -v68, -v69
	v_cvt_pk_bf16_f32 v139, -v70, -v71
	v_cvt_pk_bf16_f32 v140, -v72, -v73
	v_cvt_pk_bf16_f32 v141, -v74, -v75
	v_cvt_pk_bf16_f32 v142, -v76, -v77
	v_cvt_pk_bf16_f32 v143, -v78, -v79
	ds_write_b128 v188, v[112:115] offset:0
	ds_write_b128 v188, v[116:119] offset:1024
	ds_write_b128 v188, v[120:123] offset:2048
	ds_write_b128 v188, v[124:127] offset:3072
	ds_write_b128 v188, v[128:131] offset:4096
	ds_write_b128 v188, v[132:135] offset:5120
	ds_write_b128 v188, v[136:139] offset:6144
	ds_write_b128 v188, v[140:143] offset:7168
	s_add_u32 s26, s26, 1
	s_waitcnt lgkmcnt(0)
	v_add_u32 v184, s30, v184
	v_add_u32 v185, s30, v185
	s_sub_u32 s30, 0, s30
	v_subrev_u32 v188, s12, v188
	s_sub_u32 s12, 0, s12
	v_add_u32 v189, s13, v189
	s_sub_u32 s13, 0, s13
	s_barrier
	s_waitcnt vmcnt(5)
	v_mul_f32 v187, 0x3fb8aa3b, v2
	v_exp_f32 v187, v187
	v_lshlrev_b32 v80, 16, v4
	v_and_b32 v81, 0xffff0000, v4
	v_lshlrev_b32 v82, 16, v5
	v_and_b32 v83, 0xffff0000, v5
	v_lshlrev_b32 v84, 16, v6
	v_and_b32 v85, 0xffff0000, v6
	v_lshlrev_b32 v86, 16, v7
	v_and_b32 v87, 0xffff0000, v7
	v_lshlrev_b32 v88, 16, v8
	v_and_b32 v89, 0xffff0000, v8
	v_lshlrev_b32 v90, 16, v9
	v_and_b32 v91, 0xffff0000, v9
	v_lshlrev_b32 v92, 16, v10
	v_and_b32 v93, 0xffff0000, v10
	v_lshlrev_b32 v94, 16, v11
	v_and_b32 v95, 0xffff0000, v11
	v_lshlrev_b32 v96, 16, v12
	v_and_b32 v97, 0xffff0000, v12
	v_lshlrev_b32 v98, 16, v13
	v_and_b32 v99, 0xffff0000, v13
	v_lshlrev_b32 v100, 16, v14
	v_and_b32 v101, 0xffff0000, v14
	v_lshlrev_b32 v102, 16, v15
	v_and_b32 v103, 0xffff0000, v15
	v_lshlrev_b32 v104, 16, v190
	v_and_b32 v105, 0xffff0000, v190
	v_lshlrev_b32 v106, 16, v191
	v_and_b32 v107, 0xffff0000, v191
	v_lshlrev_b32 v108, 16, v192
	v_and_b32 v109, 0xffff0000, v192
	v_lshlrev_b32 v110, 16, v193
	v_and_b32 v111, 0xffff0000, v193
	global_load_dwordx4 v[4:7], v186, s[36:37] offset:0
	global_load_dwordx4 v[8:11], v186, s[36:37] offset:16
	global_load_dwordx4 v[12:15], v186, s[36:37] offset:2048
	global_load_dwordx4 v[190:193], v186, s[36:37] offset:2064
	global_load_dword v2, v3, s[38:39]
	s_add_u32 s36, s36, 0x4000
	s_addc_u32 s37, s37, 0
	s_add_u32 s38, s38, 4
	s_addc_u32 s39, s39, 0
	ds_read_b64 v[200:201], v184 offset:0
	ds_read_b64 v[202:203], v184 offset:16
	ds_read_b64 v[204:205], v184 offset:8448
	ds_read_b64 v[206:207], v184 offset:8464
	ds_read_b64 v[208:209], v184 offset:32
	ds_read_b64 v[210:211], v184 offset:48
	ds_read_b64 v[212:213], v184 offset:8480
	ds_read_b64 v[214:215], v184 offset:8496
	ds_read_b64 v[216:217], v184 offset:64
	ds_read_b64 v[218:219], v184 offset:80
	s_waitcnt lgkmcnt(8)
	v_mfma_f32_32x32x16_bf16 v[80:95], v[200:203], v[112:115], v[80:95]
	ds_read_b64 v[220:221], v184 offset:8512
	ds_read_b64 v[222:223], v184 offset:8528
	v_mul_f32 v16, v16, v187
	v_mul_f32 v17, v17, v187
	v_mul_f32 v18, v18, v187
	v_mul_f32 v19, v19, v187
	s_waitcnt lgkmcnt(8)
	v_mfma_f32_32x32x16_bf16 v[96:111], v[204:207], v[112:115], v[96:111]
	ds_read_b64 v[200:201], v184 offset:96
	ds_read_b64 v[202:203], v184 offset:112
	v_mul_f32 v20, v20, v187
	v_mul_f32 v21, v21, v187
	v_mul_f32 v22, v22, v187
	v_mul_f32 v23, v23, v187
	s_waitcnt lgkmcnt(8)
	v_mfma_f32_32x32x16_bf16 v[80:95], v[208:211], v[116:119], v[80:95]
	ds_read_b64 v[204:205], v184 offset:8544
	ds_read_b64 v[206:207], v184 offset:8560
	v_mul_f32 v24, v24, v187
	v_mul_f32 v25, v25, v187
	v_mul_f32 v26, v26, v187
	v_mul_f32 v27, v27, v187
	s_waitcnt lgkmcnt(8)
; __device__ __forceinline__ float lo_bf(unsigned u) { return __uint_as_float(u << 16); }
; __device__ __forceinline__ float hi_bf(unsigned u) { return __uint_as_float(u & 0xffff0000u); }
; __device__ __forceinline__ void gdn_scan_item(const Ctx& a, int l, int b, int h, int half, LAS unsigned char* lds, int variant) {
;     ...
;             for (int kb = 0; kb < 4; ++kb) {
; #pragma unroll
;                 for (int c = 0; c < 2; ++c)
; #pragma unroll
;                     for (int tb = 0; tb < 2; ++tb) {
;                         aop[c * 2 + tb] = lds_a2(Wb + (tb * 32 + l32) * 132 + kb * 32 + c * 16 + hb * 4);
;                         aop[4 + c * 2 + tb] = lds_a2(Qb + (tb * 32 + l32) * 132 + kb * 32 + c * 16 + hb * 4);
;                     }
;                 __builtin_amdgcn_sched_barrier(0);
; #pragma unroll
;                 for (int c = 0; c < 2; ++c) {
;                     bf16x8 sb = pack8(S[kb], c);
; #pragma unroll
;                     for (int tb = 0; tb < 2; ++tb) {
;                         vn[tb] = __builtin_amdgcn_mfma_f32_32x32x16_bf16(aop[c * 2 + tb], sb, vn[tb], 0, 0, 0);
;                         o[tb] = __builtin_amdgcn_mfma_f32_32x32x16_bf16(aop[4 + c * 2 + tb], sb, o[tb], 0, 0, 0);
;                     }
;                 }
;                 __builtin_amdgcn_sched_barrier(0);
;             }
;             bf16x8 vb[2][2];
; #pragma unroll
;             for (int tb = 0; tb < 2; ++tb) {
; #pragma unroll
;                 for (int r = 0; r < 16; ++r) { unsigned uw = U[tb][r >> 3][(r >> 1) & 3]; vn[tb][r] = ((r & 1) ? hi_bf(uw) : lo_bf(uw)) - vn[tb][r]; }
;                 vb[tb][0] = pack8(vn[tb], 0); vb[tb][1] = pack8(vn[tb], 1);
;             }
;             __builtin_amdgcn_sched_barrier(0);
;             { const int n1_ = (n + 1 < 128) ? n + 1 : 127; GS_LOADU(n1_); }
;             bf16x8 qop[8];
; #pragma unroll
;             for (int kb = 0; kb < 4; ++kb)
; #pragma unroll
;                 for (int tb2 = 0; tb2 < 2; ++tb2)
; #pragma unroll
;                     for (int c = 0; c < 2; ++c) aop[(kb * 2 + tb2) * 2 + c] = lds_a2(Kt + (kb * 32 + l32) * 68 + tb2 * 32 + c * 16 + hb * 4);
; #pragma unroll
;             for (int kb = 0; kb < 4; ++kb)
; #pragma unroll
;                 for (int r = 0; r < 16; ++r) S[kb][r] *= gl;
	v_mfma_f32_32x32x16_bf16 v[96:111], v[212:215], v[116:119], v[96:111]
	ds_read_b64 v[208:209], v184 offset:128
	ds_read_b64 v[210:211], v184 offset:144
	v_mul_f32 v28, v28, v187
	v_mul_f32 v29, v29, v187
	v_mul_f32 v30, v30, v187
	v_mul_f32 v31, v31, v187
	s_waitcnt lgkmcnt(8)
	v_mfma_f32_32x32x16_bf16 v[80:95], v[216:219], v[120:123], v[80:95]
	ds_read_b64 v[212:213], v184 offset:8576
	ds_read_b64 v[214:215], v184 offset:8592
	v_mul_f32 v32, v32, v187
	v_mul_f32 v33, v33, v187
	v_mul_f32 v34, v34, v187
	v_mul_f32 v35, v35, v187
	s_waitcnt lgkmcnt(8)
	v_mfma_f32_32x32x16_bf16 v[96:111], v[220:223], v[120:123], v[96:111]
	ds_read_b64 v[216:217], v184 offset:160
	ds_read_b64 v[218:219], v184 offset:176
	v_mul_f32 v36, v36, v187
	v_mul_f32 v37, v37, v187
	v_mul_f32 v38, v38, v187
	v_mul_f32 v39, v39, v187
	s_waitcnt lgkmcnt(8)
	v_mfma_f32_32x32x16_bf16 v[80:95], v[200:203], v[124:127], v[80:95]
	ds_read_b64 v[220:221], v184 offset:8608
	ds_read_b64 v[222:223], v184 offset:8624
	v_mul_f32 v40, v40, v187
	v_mul_f32 v41, v41, v187
	v_mul_f32 v42, v42, v187
	v_mul_f32 v43, v43, v187
	s_waitcnt lgkmcnt(8)
	v_mfma_f32_32x32x16_bf16 v[96:111], v[204:207], v[124:127], v[96:111]
	ds_read_b64 v[200:201], v184 offset:192
	ds_read_b64 v[202:203], v184 offset:208
	v_mul_f32 v44, v44, v187
	v_mul_f32 v45, v45, v187
	v_mul_f32 v46, v46, v187
	v_mul_f32 v47, v47, v187
	s_waitcnt lgkmcnt(8)
	v_mfma_f32_32x32x16_bf16 v[80:95], v[208:211], v[128:131], v[80:95]
	ds_read_b64 v[204:205], v184 offset:8640
	ds_read_b64 v[206:207], v184 offset:8656
	v_mul_f32 v48, v48, v187
	v_mul_f32 v49, v49, v187
	v_mul_f32 v50, v50, v187
	v_mul_f32 v51, v51, v187
	s_waitcnt lgkmcnt(8)
	v_mfma_f32_32x32x16_bf16 v[96:111], v[212:215], v[128:131], v[96:111]
	ds_read_b64 v[208:209], v184 offset:224
	ds_read_b64 v[210:211], v184 offset:240
	v_mul_f32 v52, v52, v187
	v_mul_f32 v53, v53, v187
	v_mul_f32 v54, v54, v187
	v_mul_f32 v55, v55, v187
	s_waitcnt lgkmcnt(8)
	v_mfma_f32_32x32x16_bf16 v[80:95], v[216:219], v[132:135], v[80:95]
	ds_read_b64 v[212:213], v184 offset:8672
	ds_read_b64 v[214:215], v184 offset:8688
	v_mul_f32 v56, v56, v187
	v_mul_f32 v57, v57, v187
	v_mul_f32 v58, v58, v187
	v_mul_f32 v59, v59, v187
	s_waitcnt lgkmcnt(8)
	v_mfma_f32_32x32x16_bf16 v[96:111], v[220:223], v[132:135], v[96:111]
	v_mul_f32 v60, v60, v187
	v_mul_f32 v61, v61, v187
	v_mul_f32 v62, v62, v187
	v_mul_f32 v63, v63, v187
	s_waitcnt lgkmcnt(6)
	v_mfma_f32_32x32x16_bf16 v[80:95], v[200:203], v[136:139], v[80:95]
	v_mul_f32 v64, v64, v187
	v_mul_f32 v65, v65, v187
	v_mul_f32 v66, v66, v187
	v_mul_f32 v67, v67, v187
	s_waitcnt lgkmcnt(4)
	v_mfma_f32_32x32x16_bf16 v[96:111], v[204:207], v[136:139], v[96:111]
	v_mul_f32 v68, v68, v187
	v_mul_f32 v69, v69, v187
	v_mul_f32 v70, v70, v187
	v_mul_f32 v71, v71, v187
	s_waitcnt lgkmcnt(2)
	v_mfma_f32_32x32x16_bf16 v[80:95], v[208:211], v[140:143], v[80:95]
	v_mul_f32 v72, v72, v187
	v_mul_f32 v73, v73, v187
	v_mul_f32 v74, v74, v187
	v_mul_f32 v75, v75, v187
	s_waitcnt lgkmcnt(0)
	v_mfma_f32_32x32x16_bf16 v[96:111], v[212:215], v[140:143], v[96:111]
	v_mul_f32 v76, v76, v187
	v_mul_f32 v77, v77, v187
	v_mul_f32 v78, v78, v187
	v_mul_f32 v79, v79, v187
	ds_read_b64 v[224:225], v185 offset:33792
	ds_read_b64 v[226:227], v185 offset:33808
	ds_read_b64 v[228:229], v185 offset:38144
	ds_read_b64 v[230:231], v185 offset:38160
	ds_read_b64 v[232:233], v185 offset:42496
	ds_read_b64 v[234:235], v185 offset:42512
	ds_read_b64 v[236:237], v185 offset:46848
	ds_read_b64 v[238:239], v185 offset:46864
	ds_read_b64 v[240:241], v185 offset:33824
	ds_read_b64 v[242:243], v185 offset:33840
	v_cvt_pk_bf16_f32 v146, v80, v81
	v_cvt_pk_bf16_f32 v147, v82, v83
	v_cvt_pk_bf16_f32 v148, v84, v85
	v_cvt_pk_bf16_f32 v149, v86, v87
	v_cvt_pk_bf16_f32 v150, v88, v89
	v_cvt_pk_bf16_f32 v151, v90, v91
	v_cvt_pk_bf16_f32 v152, v92, v93
	v_cvt_pk_bf16_f32 v153, v94, v95
	v_cvt_pk_bf16_f32 v154, v96, v97
	v_cvt_pk_bf16_f32 v155, v98, v99
	v_cvt_pk_bf16_f32 v156, v100, v101
	v_cvt_pk_bf16_f32 v157, v102, v103
	v_cvt_pk_bf16_f32 v158, v104, v105
	v_cvt_pk_bf16_f32 v159, v106, v107
	v_cvt_pk_bf16_f32 v160, v108, v109
	v_cvt_pk_bf16_f32 v161, v110, v111
	ds_write_b128 v189, v[146:149] offset:0
	ds_write_b128 v189, v[150:153] offset:1024
	ds_write_b128 v189, v[154:157] offset:2048
	ds_write_b128 v189, v[158:161] offset:3072
	s_waitcnt lgkmcnt(12)
; __device__ __forceinline__ bf16_t f2bf(float f) { return (bf16_t)(cvt_pk(f, 0.f) & 0xffffu); }
; #define GS_BAR() asm volatile("s_waitcnt lgkmcnt(0)\n\ts_barrier" ::: "memory")
; __device__ __forceinline__ void gdn_scan_item(const Ctx& a, int l, int b, int h, int half, LAS unsigned char* lds, int variant) {
;     ...
;             for (int kb = 0; kb < 4; ++kb)
; #pragma unroll
;                 for (int r = 0; r < 16; ++r) S[kb][r] *= gl;
;             __builtin_amdgcn_sched_barrier(0);
; #pragma unroll
;             for (int tb2 = 0; tb2 < 2; ++tb2)
; #pragma unroll
;                 for (int c = 0; c < 2; ++c)
; #pragma unroll
;                     for (int kb = 0; kb < 4; ++kb)
;                         S[kb] = __builtin_amdgcn_mfma_f32_32x32x16_bf16(aop[(kb * 2 + tb2) * 2 + c], vb[tb2][c], S[kb], 0, 0, 0);
;             __builtin_amdgcn_sched_barrier(0);
; #pragma unroll
;             for (int tb2 = 0; tb2 < 2; ++tb2)
; #pragma unroll
;                 for (int c = 0; c < 2; ++c)
; #pragma unroll
;                     for (int tb = 0; tb < 2; ++tb) qop[(tb2 * 2 + c) * 2 + tb] = lds_a2(QKb + (tb * 32 + l32) * 68 + tb2 * 32 + c * 16 + hb * 4);
;             __builtin_amdgcn_sched_barrier(0);
; #pragma unroll
;             for (int tb2 = 0; tb2 < 2; ++tb2)
; #pragma unroll
;                 for (int c = 0; c < 2; ++c)
; #pragma unroll
;                     for (int tb = 0; tb < 2; ++tb) o[tb] = __builtin_amdgcn_mfma_f32_32x32x16_bf16(qop[(tb2 * 2 + c) * 2 + tb], vb[tb2][c], o[tb], 0, 0, 0);
;             __builtin_amdgcn_sched_barrier(0);
;             {
;                 bf16_t* op = br + ((size_t)b * SEQ + n * 64) * BR + 512 + h * 128 + dv0 + l32;
; #pragma unroll
;                 for (int tb = 0; tb < 2; ++tb)
; #pragma unroll
;                     for (int r = 0; r < 16; ++r) op[(size_t)(tb * 32 + (r >> 2) * 8 + hb * 4 + (r & 3)) * BR] = f2bf(o[tb][r]);
;             }
;             GS_BAR();
;         }
;     }
;     __syncthreads();
; }
	v_mfma_f32_32x32x16_bf16 v[16:31], v[224:227], v[146:149], v[16:31]
	ds_read_b64 v[244:245], v185 offset:38176
	ds_read_b64 v[246:247], v185 offset:38192
	s_waitcnt lgkmcnt(12)
	v_mfma_f32_32x32x16_bf16 v[32:47], v[228:231], v[146:149], v[32:47]
	ds_read_b64 v[248:249], v185 offset:42528
	ds_read_b64 v[250:251], v185 offset:42544
	s_waitcnt lgkmcnt(12)
	v_mfma_f32_32x32x16_bf16 v[48:63], v[232:235], v[146:149], v[48:63]
	ds_read_b64 v[224:225], v185 offset:46880
	ds_read_b64 v[226:227], v185 offset:46896
	s_waitcnt lgkmcnt(12)
	v_mfma_f32_32x32x16_bf16 v[64:79], v[236:239], v[146:149], v[64:79]
	ds_read_b64 v[228:229], v185 offset:33856
	ds_read_b64 v[230:231], v185 offset:33872
	s_waitcnt lgkmcnt(12)
	v_mfma_f32_32x32x16_bf16 v[16:31], v[240:243], v[150:153], v[16:31]
	ds_read_b64 v[232:233], v185 offset:38208
	ds_read_b64 v[234:235], v185 offset:38224
	s_waitcnt lgkmcnt(8)
	v_mfma_f32_32x32x16_bf16 v[32:47], v[244:247], v[150:153], v[32:47]
	ds_read_b64 v[236:237], v185 offset:42560
	ds_read_b64 v[238:239], v185 offset:42576
	s_waitcnt lgkmcnt(8)
	v_mfma_f32_32x32x16_bf16 v[48:63], v[248:251], v[150:153], v[48:63]
	ds_read_b64 v[240:241], v185 offset:46912
	ds_read_b64 v[242:243], v185 offset:46928
	s_waitcnt lgkmcnt(8)
	v_mfma_f32_32x32x16_bf16 v[64:79], v[224:227], v[150:153], v[64:79]
	ds_read_b64 v[244:245], v185 offset:33888
	ds_read_b64 v[246:247], v185 offset:33904
	s_waitcnt lgkmcnt(8)
	v_mfma_f32_32x32x16_bf16 v[16:31], v[228:231], v[154:157], v[16:31]
	ds_read_b64 v[248:249], v185 offset:38240
	ds_read_b64 v[250:251], v185 offset:38256
	s_waitcnt lgkmcnt(8)
	v_mfma_f32_32x32x16_bf16 v[32:47], v[232:235], v[154:157], v[32:47]
	ds_read_b64 v[224:225], v185 offset:42592
	ds_read_b64 v[226:227], v185 offset:42608
	s_waitcnt lgkmcnt(8)
	v_mfma_f32_32x32x16_bf16 v[48:63], v[236:239], v[154:157], v[48:63]
	ds_read_b64 v[228:229], v185 offset:46944
	ds_read_b64 v[230:231], v185 offset:46960
	s_waitcnt lgkmcnt(8)
	v_mfma_f32_32x32x16_bf16 v[64:79], v[240:243], v[154:157], v[64:79]
	s_waitcnt lgkmcnt(6)
	v_mfma_f32_32x32x16_bf16 v[16:31], v[244:247], v[158:161], v[16:31]
	s_waitcnt lgkmcnt(4)
	v_mfma_f32_32x32x16_bf16 v[32:47], v[248:251], v[158:161], v[32:47]
	s_waitcnt lgkmcnt(2)
	v_mfma_f32_32x32x16_bf16 v[48:63], v[224:227], v[158:161], v[48:63]
	s_waitcnt lgkmcnt(0)
	v_mfma_f32_32x32x16_bf16 v[64:79], v[228:231], v[158:161], v[64:79]
	s_nop 5
	v_cvt_pk_bf16_f32 v112, -v16, -v17
	v_cvt_pk_bf16_f32 v113, -v18, -v19
	v_cvt_pk_bf16_f32 v114, -v20, -v21
	v_cvt_pk_bf16_f32 v115, -v22, -v23
	v_cvt_pk_bf16_f32 v116, -v24, -v25
	v_cvt_pk_bf16_f32 v117, -v26, -v27
	v_cvt_pk_bf16_f32 v118, -v28, -v29
	v_cvt_pk_bf16_f32 v119, -v30, -v31
	v_cvt_pk_bf16_f32 v120, -v32, -v33
	v_cvt_pk_bf16_f32 v121, -v34, -v35
	v_cvt_pk_bf16_f32 v122, -v36, -v37
	v_cvt_pk_bf16_f32 v123, -v38, -v39
	v_cvt_pk_bf16_f32 v124, -v40, -v41
	v_cvt_pk_bf16_f32 v125, -v42, -v43
	v_cvt_pk_bf16_f32 v126, -v44, -v45
	v_cvt_pk_bf16_f32 v127, -v46, -v47
	v_cvt_pk_bf16_f32 v128, -v48, -v49
	v_cvt_pk_bf16_f32 v129, -v50, -v51
	v_cvt_pk_bf16_f32 v130, -v52, -v53
	v_cvt_pk_bf16_f32 v131, -v54, -v55
	v_cvt_pk_bf16_f32 v132, -v56, -v57
	v_cvt_pk_bf16_f32 v133, -v58, -v59
	v_cvt_pk_bf16_f32 v134, -v60, -v61
	v_cvt_pk_bf16_f32 v135, -v62, -v63
	v_cvt_pk_bf16_f32 v136, -v64, -v65
	v_cvt_pk_bf16_f32 v137, -v66, -v67
	v_cvt_pk_bf16_f32 v138, -v68, -v69
	v_cvt_pk_bf16_f32 v139, -v70, -v71
	v_cvt_pk_bf16_f32 v140, -v72, -v73
	v_cvt_pk_bf16_f32 v141, -v74, -v75
	v_cvt_pk_bf16_f32 v142, -v76, -v77
	v_cvt_pk_bf16_f32 v143, -v78, -v79
	ds_write_b128 v188, v[112:115] offset:0
	ds_write_b128 v188, v[116:119] offset:1024
	ds_write_b128 v188, v[120:123] offset:2048
	ds_write_b128 v188, v[124:127] offset:3072
	ds_write_b128 v188, v[128:131] offset:4096
	ds_write_b128 v188, v[132:135] offset:5120
	ds_write_b128 v188, v[136:139] offset:6144
	ds_write_b128 v188, v[140:143] offset:7168
	s_add_u32 s26, s26, 1
	s_waitcnt lgkmcnt(0)
	v_add_u32 v184, s30, v184
	v_add_u32 v185, s30, v185
	s_sub_u32 s30, 0, s30
	v_subrev_u32 v188, s12, v188
	s_sub_u32 s12, 0, s12
	v_add_u32 v189, s13, v189
	s_sub_u32 s13, 0, s13
	s_barrier
	s_cmp_lt_u32 s26, 0x80
	s_cbranch_scc1 .Lsc0_loop
	s_waitcnt vmcnt(0)
	s_branch .LBB0_156
